# instruction selection (v_pk_mul/v_pk_add) in the VALU-bound SwiGLU GEMM epilogue: 16 packed ops + 16 transcendentals per store instead of 32 scalar mul/add + 16, same arithmetic order
# baseline (speedup 1.0000x reference)
.LBB0_469:
	v_readlane_b32 s4, v242, 42
	v_readlane_b32 s5, v242, 43
	v_lshl_add_u32 v146, s2, 8, v152
	s_andn2_b64 vcc, exec, s[4:5]
	s_mov_b64 s[10:11], -1
	s_cbranch_vccnz .LBB0_471
	v_mov_b32_e32 v252, 0xbfb8aa3b
	v_mov_b32_e32 v253, 0xbfb8aa3b
	v_mov_b32_e32 v254, 1.0
	v_mov_b32_e32 v255, 1.0
	v_lshl_or_b32 v134, s92, 7, v154
	v_ashrrev_i32_e32 v135, 31, v134
	v_mov_b64_e32 v[132:133], s[18:19]
	v_mad_i64_i32 v[156:157], s[4:5], v146, s37, v[132:133]
	v_lshlrev_b64 v[134:135], 1, v[134:135]
	v_lshl_add_u64 v[156:157], v[156:157], 0, v[134:135]
	v_pk_mul_f32 v[244:245], v[128:129], v[252:253]
	v_pk_mul_f32 v[246:247], v[130:131], v[252:253]
	v_pk_mul_f32 v[248:249], v[124:125], v[252:253]
	v_pk_mul_f32 v[250:251], v[126:127], v[252:253]
	v_exp_f32_e32 v244, v244
	v_exp_f32_e32 v245, v245
	v_exp_f32_e32 v246, v246
	v_exp_f32_e32 v247, v247
	v_exp_f32_e32 v248, v248
	v_exp_f32_e32 v249, v249
	v_exp_f32_e32 v250, v250
	v_exp_f32_e32 v251, v251
	v_pk_add_f32 v[244:245], v[244:245], v[254:255]
	v_pk_add_f32 v[246:247], v[246:247], v[254:255]
	v_pk_add_f32 v[248:249], v[248:249], v[254:255]
	v_pk_add_f32 v[250:251], v[250:251], v[254:255]
	v_rcp_f32_e32 v244, v244
	v_rcp_f32_e32 v245, v245
	v_rcp_f32_e32 v246, v246
	v_rcp_f32_e32 v247, v247
	v_rcp_f32_e32 v248, v248
	v_rcp_f32_e32 v249, v249
	v_rcp_f32_e32 v250, v250
	v_rcp_f32_e32 v251, v251
	v_pk_mul_f32 v[244:245], v[128:129], v[244:245]
	v_pk_mul_f32 v[246:247], v[130:131], v[246:247]
	v_pk_mul_f32 v[248:249], v[124:125], v[248:249]
	v_pk_mul_f32 v[250:251], v[126:127], v[250:251]
	v_pk_mul_f32 v[244:245], v[244:245], v[120:121]
	v_pk_mul_f32 v[246:247], v[246:247], v[122:123]
	v_pk_mul_f32 v[248:249], v[248:249], v[116:117]
	v_pk_mul_f32 v[250:251], v[250:251], v[118:119]
	v_cvt_pk_bf16_f32 v148, v244, v245
	v_cvt_pk_bf16_f32 v149, v246, v247
	v_cvt_pk_bf16_f32 v150, v248, v249
	v_cvt_pk_bf16_f32 v151, v250, v251
	global_store_dwordx4 v[156:157], v[148:151], off
	v_or_b32_e32 v147, 16, v146
	v_mad_i64_i32 v[156:157], s[4:5], v147, s37, v[132:133]
	v_lshl_add_u64 v[156:157], v[156:157], 0, v[134:135]
	v_pk_mul_f32 v[244:245], v[112:113], v[252:253]
	v_pk_mul_f32 v[246:247], v[114:115], v[252:253]
	v_pk_mul_f32 v[248:249], v[108:109], v[252:253]
	v_pk_mul_f32 v[250:251], v[110:111], v[252:253]
	v_exp_f32_e32 v244, v244
	v_exp_f32_e32 v245, v245
	v_exp_f32_e32 v246, v246
	v_exp_f32_e32 v247, v247
	v_exp_f32_e32 v248, v248
	v_exp_f32_e32 v249, v249
	v_exp_f32_e32 v250, v250
	v_exp_f32_e32 v251, v251
	v_pk_add_f32 v[244:245], v[244:245], v[254:255]
	v_pk_add_f32 v[246:247], v[246:247], v[254:255]
	v_pk_add_f32 v[248:249], v[248:249], v[254:255]
	v_pk_add_f32 v[250:251], v[250:251], v[254:255]
	v_rcp_f32_e32 v244, v244
	v_rcp_f32_e32 v245, v245
	v_rcp_f32_e32 v246, v246
	v_rcp_f32_e32 v247, v247
	v_rcp_f32_e32 v248, v248
	v_rcp_f32_e32 v249, v249
	v_rcp_f32_e32 v250, v250
	v_rcp_f32_e32 v251, v251
	v_pk_mul_f32 v[244:245], v[112:113], v[244:245]
	v_pk_mul_f32 v[246:247], v[114:115], v[246:247]
	v_pk_mul_f32 v[248:249], v[108:109], v[248:249]
	v_pk_mul_f32 v[250:251], v[110:111], v[250:251]
	v_pk_mul_f32 v[244:245], v[244:245], v[104:105]
	v_pk_mul_f32 v[246:247], v[246:247], v[106:107]
	v_pk_mul_f32 v[248:249], v[248:249], v[100:101]
	v_pk_mul_f32 v[250:251], v[250:251], v[102:103]
	v_cvt_pk_bf16_f32 v148, v244, v245
	v_cvt_pk_bf16_f32 v149, v246, v247
	v_cvt_pk_bf16_f32 v150, v248, v249
	v_cvt_pk_bf16_f32 v151, v250, v251
	global_store_dwordx4 v[156:157], v[148:151], off
	v_or_b32_e32 v147, 32, v146
	v_mad_i64_i32 v[156:157], s[4:5], v147, s37, v[132:133]
	v_lshl_add_u64 v[156:157], v[156:157], 0, v[134:135]
	v_pk_mul_f32 v[244:245], v[96:97], v[252:253]
	v_pk_mul_f32 v[246:247], v[98:99], v[252:253]
	v_pk_mul_f32 v[248:249], v[92:93], v[252:253]
	v_pk_mul_f32 v[250:251], v[94:95], v[252:253]
	v_exp_f32_e32 v244, v244
	v_exp_f32_e32 v245, v245
	v_exp_f32_e32 v246, v246
	v_exp_f32_e32 v247, v247
	v_exp_f32_e32 v248, v248
	v_exp_f32_e32 v249, v249
	v_exp_f32_e32 v250, v250
	v_exp_f32_e32 v251, v251
	v_pk_add_f32 v[244:245], v[244:245], v[254:255]
	v_pk_add_f32 v[246:247], v[246:247], v[254:255]
	v_pk_add_f32 v[248:249], v[248:249], v[254:255]
	v_pk_add_f32 v[250:251], v[250:251], v[254:255]
	v_rcp_f32_e32 v244, v244
	v_rcp_f32_e32 v245, v245
	v_rcp_f32_e32 v246, v246
	v_rcp_f32_e32 v247, v247
	v_rcp_f32_e32 v248, v248
	v_rcp_f32_e32 v249, v249
	v_rcp_f32_e32 v250, v250
	v_rcp_f32_e32 v251, v251
	v_pk_mul_f32 v[244:245], v[96:97], v[244:245]
	v_pk_mul_f32 v[246:247], v[98:99], v[246:247]
	v_pk_mul_f32 v[248:249], v[92:93], v[248:249]
	v_pk_mul_f32 v[250:251], v[94:95], v[250:251]
	v_pk_mul_f32 v[244:245], v[244:245], v[88:89]
	v_pk_mul_f32 v[246:247], v[246:247], v[90:91]
	v_pk_mul_f32 v[248:249], v[248:249], v[84:85]
	v_pk_mul_f32 v[250:251], v[250:251], v[86:87]
	v_cvt_pk_bf16_f32 v148, v244, v245
	v_cvt_pk_bf16_f32 v149, v246, v247
	v_cvt_pk_bf16_f32 v150, v248, v249
	v_cvt_pk_bf16_f32 v151, v250, v251
	global_store_dwordx4 v[156:157], v[148:151], off
	v_or_b32_e32 v147, 48, v146
	v_mad_i64_i32 v[156:157], s[4:5], v147, s37, v[132:133]
	v_lshl_add_u64 v[156:157], v[156:157], 0, v[134:135]
	v_pk_mul_f32 v[244:245], v[80:81], v[252:253]
	v_pk_mul_f32 v[246:247], v[82:83], v[252:253]
	v_pk_mul_f32 v[248:249], v[76:77], v[252:253]
	v_pk_mul_f32 v[250:251], v[78:79], v[252:253]
	v_exp_f32_e32 v244, v244
	v_exp_f32_e32 v245, v245
	v_exp_f32_e32 v246, v246
	v_exp_f32_e32 v247, v247
	v_exp_f32_e32 v248, v248
	v_exp_f32_e32 v249, v249
	v_exp_f32_e32 v250, v250
	v_exp_f32_e32 v251, v251
	v_pk_add_f32 v[244:245], v[244:245], v[254:255]
	v_pk_add_f32 v[246:247], v[246:247], v[254:255]
	v_pk_add_f32 v[248:249], v[248:249], v[254:255]
	v_pk_add_f32 v[250:251], v[250:251], v[254:255]
	v_rcp_f32_e32 v244, v244
	v_rcp_f32_e32 v245, v245
	v_rcp_f32_e32 v246, v246
	v_rcp_f32_e32 v247, v247
	v_rcp_f32_e32 v248, v248
	v_rcp_f32_e32 v249, v249
	v_rcp_f32_e32 v250, v250
	v_rcp_f32_e32 v251, v251
	v_pk_mul_f32 v[244:245], v[80:81], v[244:245]
	v_pk_mul_f32 v[246:247], v[82:83], v[246:247]
	v_pk_mul_f32 v[248:249], v[76:77], v[248:249]
	v_pk_mul_f32 v[250:251], v[78:79], v[250:251]
	v_pk_mul_f32 v[244:245], v[244:245], v[72:73]
	v_pk_mul_f32 v[246:247], v[246:247], v[74:75]
	v_pk_mul_f32 v[248:249], v[248:249], v[68:69]
	v_pk_mul_f32 v[250:251], v[250:251], v[70:71]
	v_cvt_pk_bf16_f32 v148, v244, v245
	v_cvt_pk_bf16_f32 v149, v246, v247
	v_cvt_pk_bf16_f32 v150, v248, v249
	v_cvt_pk_bf16_f32 v151, v250, v251
	global_store_dwordx4 v[156:157], v[148:151], off
	v_add_u32_e32 v147, 0x80, v146
	v_mad_i64_i32 v[156:157], s[4:5], v147, s37, v[132:133]
	v_lshl_add_u64 v[156:157], v[156:157], 0, v[134:135]
	v_pk_mul_f32 v[244:245], v[64:65], v[252:253]
	v_pk_mul_f32 v[246:247], v[66:67], v[252:253]
	v_pk_mul_f32 v[248:249], v[60:61], v[252:253]
	v_pk_mul_f32 v[250:251], v[62:63], v[252:253]
	v_exp_f32_e32 v244, v244
	v_exp_f32_e32 v245, v245
	v_exp_f32_e32 v246, v246
	v_exp_f32_e32 v247, v247
	v_exp_f32_e32 v248, v248
	v_exp_f32_e32 v249, v249
	v_exp_f32_e32 v250, v250
	v_exp_f32_e32 v251, v251
	v_pk_add_f32 v[244:245], v[244:245], v[254:255]
	v_pk_add_f32 v[246:247], v[246:247], v[254:255]
	v_pk_add_f32 v[248:249], v[248:249], v[254:255]
	v_pk_add_f32 v[250:251], v[250:251], v[254:255]
	v_rcp_f32_e32 v244, v244
	v_rcp_f32_e32 v245, v245
	v_rcp_f32_e32 v246, v246
	v_rcp_f32_e32 v247, v247
	v_rcp_f32_e32 v248, v248
	v_rcp_f32_e32 v249, v249
	v_rcp_f32_e32 v250, v250
	v_rcp_f32_e32 v251, v251
	v_pk_mul_f32 v[244:245], v[64:65], v[244:245]
	v_pk_mul_f32 v[246:247], v[66:67], v[246:247]
	v_pk_mul_f32 v[248:249], v[60:61], v[248:249]
	v_pk_mul_f32 v[250:251], v[62:63], v[250:251]
	v_pk_mul_f32 v[244:245], v[244:245], v[56:57]
	v_pk_mul_f32 v[246:247], v[246:247], v[58:59]
	v_pk_mul_f32 v[248:249], v[248:249], v[52:53]
	v_pk_mul_f32 v[250:251], v[250:251], v[54:55]
	v_cvt_pk_bf16_f32 v148, v244, v245
	v_cvt_pk_bf16_f32 v149, v246, v247
	v_cvt_pk_bf16_f32 v150, v248, v249
	v_cvt_pk_bf16_f32 v151, v250, v251
	global_store_dwordx4 v[156:157], v[148:151], off
	v_add_u32_e32 v147, 0x90, v146
	v_mad_i64_i32 v[156:157], s[4:5], v147, s37, v[132:133]
	v_lshl_add_u64 v[156:157], v[156:157], 0, v[134:135]
	v_pk_mul_f32 v[244:245], v[48:49], v[252:253]
	v_pk_mul_f32 v[246:247], v[50:51], v[252:253]
	v_pk_mul_f32 v[248:249], v[44:45], v[252:253]
	v_pk_mul_f32 v[250:251], v[46:47], v[252:253]
	v_exp_f32_e32 v244, v244
	v_exp_f32_e32 v245, v245
	v_exp_f32_e32 v246, v246
	v_exp_f32_e32 v247, v247
	v_exp_f32_e32 v248, v248
	v_exp_f32_e32 v249, v249
	v_exp_f32_e32 v250, v250
	v_exp_f32_e32 v251, v251
	v_pk_add_f32 v[244:245], v[244:245], v[254:255]
	v_pk_add_f32 v[246:247], v[246:247], v[254:255]
	v_pk_add_f32 v[248:249], v[248:249], v[254:255]
	v_pk_add_f32 v[250:251], v[250:251], v[254:255]
	v_rcp_f32_e32 v244, v244
	v_rcp_f32_e32 v245, v245
	v_rcp_f32_e32 v246, v246
	v_rcp_f32_e32 v247, v247
	v_rcp_f32_e32 v248, v248
	v_rcp_f32_e32 v249, v249
	v_rcp_f32_e32 v250, v250
	v_rcp_f32_e32 v251, v251
	v_pk_mul_f32 v[244:245], v[48:49], v[244:245]
	v_pk_mul_f32 v[246:247], v[50:51], v[246:247]
	v_pk_mul_f32 v[248:249], v[44:45], v[248:249]
	v_pk_mul_f32 v[250:251], v[46:47], v[250:251]
	v_pk_mul_f32 v[244:245], v[244:245], v[40:41]
	v_pk_mul_f32 v[246:247], v[246:247], v[42:43]
	v_pk_mul_f32 v[248:249], v[248:249], v[36:37]
	v_pk_mul_f32 v[250:251], v[250:251], v[38:39]
	v_cvt_pk_bf16_f32 v148, v244, v245
	v_cvt_pk_bf16_f32 v149, v246, v247
	v_cvt_pk_bf16_f32 v150, v248, v249
	v_cvt_pk_bf16_f32 v151, v250, v251
	global_store_dwordx4 v[156:157], v[148:151], off
	v_add_u32_e32 v147, 0xa0, v146
	v_mad_i64_i32 v[156:157], s[4:5], v147, s37, v[132:133]
	v_lshl_add_u64 v[156:157], v[156:157], 0, v[134:135]
	v_pk_mul_f32 v[244:245], v[32:33], v[252:253]
	v_pk_mul_f32 v[246:247], v[34:35], v[252:253]
	v_pk_mul_f32 v[248:249], v[28:29], v[252:253]
	v_pk_mul_f32 v[250:251], v[30:31], v[252:253]
	v_exp_f32_e32 v244, v244
	v_exp_f32_e32 v245, v245
	v_exp_f32_e32 v246, v246
	v_exp_f32_e32 v247, v247
	v_exp_f32_e32 v248, v248
	v_exp_f32_e32 v249, v249
	v_exp_f32_e32 v250, v250
	v_exp_f32_e32 v251, v251
	v_pk_add_f32 v[244:245], v[244:245], v[254:255]
	v_pk_add_f32 v[246:247], v[246:247], v[254:255]
	v_pk_add_f32 v[248:249], v[248:249], v[254:255]
	v_pk_add_f32 v[250:251], v[250:251], v[254:255]
	v_rcp_f32_e32 v244, v244
	v_rcp_f32_e32 v245, v245
	v_rcp_f32_e32 v246, v246
	v_rcp_f32_e32 v247, v247
	v_rcp_f32_e32 v248, v248
	v_rcp_f32_e32 v249, v249
	v_rcp_f32_e32 v250, v250
	v_rcp_f32_e32 v251, v251
	v_pk_mul_f32 v[244:245], v[32:33], v[244:245]
	v_pk_mul_f32 v[246:247], v[34:35], v[246:247]
	v_pk_mul_f32 v[248:249], v[28:29], v[248:249]
	v_pk_mul_f32 v[250:251], v[30:31], v[250:251]
	v_pk_mul_f32 v[244:245], v[244:245], v[24:25]
	v_pk_mul_f32 v[246:247], v[246:247], v[26:27]
	v_pk_mul_f32 v[248:249], v[248:249], v[20:21]
	v_pk_mul_f32 v[250:251], v[250:251], v[22:23]
	v_cvt_pk_bf16_f32 v148, v244, v245
	v_cvt_pk_bf16_f32 v149, v246, v247
	v_cvt_pk_bf16_f32 v150, v248, v249
	v_cvt_pk_bf16_f32 v151, v250, v251
	global_store_dwordx4 v[156:157], v[148:151], off
	v_add_u32_e32 v147, 0xb0, v146
	v_mad_i64_i32 v[132:133], s[4:5], v147, s37, v[132:133]
	v_lshl_add_u64 v[132:133], v[132:133], 0, v[134:135]
	s_mov_b64 s[10:11], 0
	v_pk_mul_f32 v[244:245], v[16:17], v[252:253]
	v_pk_mul_f32 v[246:247], v[18:19], v[252:253]
	v_pk_mul_f32 v[248:249], v[12:13], v[252:253]
	v_pk_mul_f32 v[250:251], v[14:15], v[252:253]
	v_exp_f32_e32 v244, v244
	v_exp_f32_e32 v245, v245
	v_exp_f32_e32 v246, v246
	v_exp_f32_e32 v247, v247
	v_exp_f32_e32 v248, v248
	v_exp_f32_e32 v249, v249
	v_exp_f32_e32 v250, v250
	v_exp_f32_e32 v251, v251
	v_pk_add_f32 v[244:245], v[244:245], v[254:255]
	v_pk_add_f32 v[246:247], v[246:247], v[254:255]
	v_pk_add_f32 v[248:249], v[248:249], v[254:255]
	v_pk_add_f32 v[250:251], v[250:251], v[254:255]
	v_rcp_f32_e32 v244, v244
	v_rcp_f32_e32 v245, v245
	v_rcp_f32_e32 v246, v246
	v_rcp_f32_e32 v247, v247
	v_rcp_f32_e32 v248, v248
	v_rcp_f32_e32 v249, v249
	v_rcp_f32_e32 v250, v250
	v_rcp_f32_e32 v251, v251
	v_pk_mul_f32 v[244:245], v[16:17], v[244:245]
	v_pk_mul_f32 v[246:247], v[18:19], v[246:247]
	v_pk_mul_f32 v[248:249], v[12:13], v[248:249]
	v_pk_mul_f32 v[250:251], v[14:15], v[250:251]
	v_pk_mul_f32 v[244:245], v[244:245], v[6:7]
	v_pk_mul_f32 v[246:247], v[246:247], v[8:9]
	v_pk_mul_f32 v[248:249], v[248:249], v[2:3]
	v_pk_mul_f32 v[250:251], v[250:251], v[4:5]
	v_cvt_pk_bf16_f32 v148, v244, v245
	v_cvt_pk_bf16_f32 v149, v246, v247
	v_cvt_pk_bf16_f32 v150, v248, v249
	v_cvt_pk_bf16_f32 v151, v250, v251
	global_store_dwordx4 v[132:133], v[148:151], off
